# conformer conv sample rows hand-written: 4 channels per thread, dwordx4 accesses, state rows streamed through a 12-quad ring
# speedup vs baseline: 1.0050x; 1.0009x over previous
; __device__ __forceinline__ void cf_sample_item(const bf16_t* PROJ, int s, int c, const float* st, const float* cw, const float* cb, bf16_t* CONVOUT, float* state_out) {
;     f32x2 xp[34], w[31];
;     unsigned uv[4];
; #pragma unroll
;     for (int j = 0; j < 30; ++j) xp[j] = *(const f32x2*)(st + j * DM + c);
; #pragma unroll
;     for (int t = 0; t < 4; ++t) uv[t] = *(const unsigned*)(PROJ + (size_t)(MP + 4 * s + t) * NPROJ + CUCF + c);
; #pragma unroll
;     for (int i = 0; i < 31; ++i) w[i] = *(const f32x2*)(cw + i * DM + c);
;     const f32x2 bias = *(const f32x2*)(cb + c);
; __global__ void __launch_bounds__(512, 2) mk_fwd(Args args) {
;     ...
;             for (int it2 = bx; it2 < 256; it2 += G) { const int s = it2 >> 1, c = (it2 & 1) * 1024 + tid * 2;
;                 cf_sample_item(PROJ, s, c, state_cfc + (size_t)s * 30 * DM, cf_conv_w, cf_conv_b, CONVOUT, out + O_SCFC + (size_t)s * 30 * DM); }
.LBB0_293:
	s_load_dwordx4 s[88:91], s[96:97], 0xd8
	v_readlane_b32 s74, v253, 12
	s_cmpk_gt_i32 s2, 0xff
	v_readlane_b32 s75, v253, 13
	s_cbranch_scc1 .LBB0_296
	v_readfirstlane_b32 s0, v172
	s_load_dwordx2 s[26:27], s[22:23], 0x20
	s_lshr_b32 s0, s0, 6
	s_cmp_ge_u32 s0, 4
	s_cbranch_scc1 .Lcfs_done
	v_lshlrev_b32_e32 v224, 4, v172
	v_lshlrev_b32_e32 v225, 3, v172
	s_mov_b32 s1, s2
	s_waitcnt lgkmcnt(0)
.Lcfs_item:
	s_lshr_b32 s4, s1, 1
	s_and_b32 s5, s1, 1
	s_lshl_b32 s28, s5, 12
	s_lshl_b32 s29, s5, 11
	s_mul_i32 s30, s4, 245760
	s_add_u32 s30, s30, s28
	s_add_u32 s12, s26, s30
	s_addc_u32 s13, s27, 0
	s_add_u32 s14, s16, 0xcdea000
	s_addc_u32 s15, s17, 0
	s_add_u32 s14, s14, s30
	s_addc_u32 s15, s15, 0
	s_lshl_b32 s31, s4, 2
	s_add_u32 s31, s31, 8192
	s_mul_hi_u32 s35, s31, 18944
	s_mul_i32 s34, s31, 18944
	s_add_u32 s34, s34, s3
	s_addc_u32 s35, s35, s72
	s_add_u32 s34, s34, 10240
	s_addc_u32 s35, s35, 0
	s_add_u32 s34, s34, s29
	s_addc_u32 s35, s35, 0
	s_lshl_b32 s33, s31, 12
	s_add_u32 s36, s6, s33
	s_addc_u32 s37, s7, 0
	s_add_u32 s36, s36, s29
	s_addc_u32 s37, s37, 0
	s_add_u32 s38, s8, s28
	s_addc_u32 s39, s9, 0
	s_add_u32 s40, s10, s28
	s_addc_u32 s41, s11, 0
	global_load_dwordx2 v[174:175], v225, s[34:35]
	s_add_u32 s34, s34, 18944
	s_addc_u32 s35, s35, 0
	global_load_dwordx2 v[176:177], v225, s[34:35]
	s_add_u32 s34, s34, 18944
	s_addc_u32 s35, s35, 0
	global_load_dwordx2 v[178:179], v225, s[34:35]
	s_add_u32 s34, s34, 18944
	s_addc_u32 s35, s35, 0
	global_load_dwordx2 v[180:181], v225, s[34:35]
	global_load_dwordx4 v[220:223], v224, s[40:41]
	global_load_dwordx4 v[0:3], v224, s[38:39]
	s_add_u32 s38, s38, 0x2000
	s_addc_u32 s39, s39, 0
	global_load_dwordx4 v[4:7], v224, s[38:39]
	s_add_u32 s38, s38, 0x2000
	s_addc_u32 s39, s39, 0
	global_load_dwordx4 v[8:11], v224, s[38:39]
	s_add_u32 s38, s38, 0x2000
	s_addc_u32 s39, s39, 0
	global_load_dwordx4 v[12:15], v224, s[38:39]
	s_add_u32 s38, s38, 0x2000
	s_addc_u32 s39, s39, 0
	global_load_dwordx4 v[16:19], v224, s[38:39]
	s_add_u32 s38, s38, 0x2000
	s_addc_u32 s39, s39, 0
	global_load_dwordx4 v[20:23], v224, s[38:39]
	s_add_u32 s38, s38, 0x2000
	s_addc_u32 s39, s39, 0
	global_load_dwordx4 v[24:27], v224, s[38:39]
	s_add_u32 s38, s38, 0x2000
	s_addc_u32 s39, s39, 0
	global_load_dwordx4 v[28:31], v224, s[38:39]
	s_add_u32 s38, s38, 0x2000
	s_addc_u32 s39, s39, 0
	global_load_dwordx4 v[32:35], v224, s[38:39]
	s_add_u32 s38, s38, 0x2000
	s_addc_u32 s39, s39, 0
	global_load_dwordx4 v[36:39], v224, s[38:39]
	s_add_u32 s38, s38, 0x2000
	s_addc_u32 s39, s39, 0
	global_load_dwordx4 v[40:43], v224, s[38:39]
	s_add_u32 s38, s38, 0x2000
	s_addc_u32 s39, s39, 0
	global_load_dwordx4 v[44:47], v224, s[38:39]
	s_add_u32 s38, s38, 0x2000
	s_addc_u32 s39, s39, 0
	global_load_dwordx4 v[48:51], v224, s[38:39]
	s_add_u32 s38, s38, 0x2000
	s_addc_u32 s39, s39, 0
	global_load_dwordx4 v[52:55], v224, s[38:39]
	s_add_u32 s38, s38, 0x2000
	s_addc_u32 s39, s39, 0
	global_load_dwordx4 v[56:59], v224, s[38:39]
	s_add_u32 s38, s38, 0x2000
	s_addc_u32 s39, s39, 0
	global_load_dwordx4 v[60:63], v224, s[38:39]
	s_add_u32 s38, s38, 0x2000
	s_addc_u32 s39, s39, 0
	global_load_dwordx4 v[64:67], v224, s[38:39]
	s_add_u32 s38, s38, 0x2000
	s_addc_u32 s39, s39, 0
	global_load_dwordx4 v[68:71], v224, s[38:39]
	s_add_u32 s38, s38, 0x2000
	s_addc_u32 s39, s39, 0
	global_load_dwordx4 v[72:75], v224, s[38:39]
	s_add_u32 s38, s38, 0x2000
	s_addc_u32 s39, s39, 0
	global_load_dwordx4 v[76:79], v224, s[38:39]
	s_add_u32 s38, s38, 0x2000
	s_addc_u32 s39, s39, 0
	global_load_dwordx4 v[80:83], v224, s[38:39]
	s_add_u32 s38, s38, 0x2000
	s_addc_u32 s39, s39, 0
	global_load_dwordx4 v[84:87], v224, s[38:39]
	s_add_u32 s38, s38, 0x2000
	s_addc_u32 s39, s39, 0
	global_load_dwordx4 v[88:91], v224, s[38:39]
	s_add_u32 s38, s38, 0x2000
	s_addc_u32 s39, s39, 0
	global_load_dwordx4 v[92:95], v224, s[38:39]
	s_add_u32 s38, s38, 0x2000
	s_addc_u32 s39, s39, 0
	global_load_dwordx4 v[96:99], v224, s[38:39]
	s_add_u32 s38, s38, 0x2000
	s_addc_u32 s39, s39, 0
	global_load_dwordx4 v[100:103], v224, s[38:39]
	s_add_u32 s38, s38, 0x2000
	s_addc_u32 s39, s39, 0
	global_load_dwordx4 v[104:107], v224, s[38:39]
	s_add_u32 s38, s38, 0x2000
	s_addc_u32 s39, s39, 0
	global_load_dwordx4 v[108:111], v224, s[38:39]
	s_add_u32 s38, s38, 0x2000
	s_addc_u32 s39, s39, 0
	global_load_dwordx4 v[112:115], v224, s[38:39]
	s_add_u32 s38, s38, 0x2000
	s_addc_u32 s39, s39, 0
	global_load_dwordx4 v[116:119], v224, s[38:39]
	s_add_u32 s38, s38, 0x2000
	s_addc_u32 s39, s39, 0
	global_load_dwordx4 v[120:123], v224, s[38:39]
	global_load_dwordx4 v[124:127], v224, s[12:13]
	s_add_u32 s12, s12, 0x2000
	s_addc_u32 s13, s13, 0
	global_load_dwordx4 v[128:131], v224, s[12:13]
	s_add_u32 s12, s12, 0x2000
	s_addc_u32 s13, s13, 0
	global_load_dwordx4 v[132:135], v224, s[12:13]
	s_add_u32 s12, s12, 0x2000
	s_addc_u32 s13, s13, 0
	global_load_dwordx4 v[136:139], v224, s[12:13]
	s_add_u32 s12, s12, 0x2000
	s_addc_u32 s13, s13, 0
	global_load_dwordx4 v[140:143], v224, s[12:13]
	s_add_u32 s12, s12, 0x2000
	s_addc_u32 s13, s13, 0
	global_load_dwordx4 v[144:147], v224, s[12:13]
	s_add_u32 s12, s12, 0x2000
	s_addc_u32 s13, s13, 0
	global_load_dwordx4 v[148:151], v224, s[12:13]
	s_add_u32 s12, s12, 0x2000
	s_addc_u32 s13, s13, 0
	global_load_dwordx4 v[152:155], v224, s[12:13]
	s_add_u32 s12, s12, 0x2000
	s_addc_u32 s13, s13, 0
	global_load_dwordx4 v[156:159], v224, s[12:13]
	s_add_u32 s12, s12, 0x2000
	s_addc_u32 s13, s13, 0
	global_load_dwordx4 v[160:163], v224, s[12:13]
	s_add_u32 s12, s12, 0x2000
	s_addc_u32 s13, s13, 0
	global_load_dwordx4 v[164:167], v224, s[12:13]
	s_add_u32 s12, s12, 0x2000
	s_addc_u32 s13, s13, 0
	global_load_dwordx4 v[168:171], v224, s[12:13]
	s_add_u32 s12, s12, 0x2000
	s_addc_u32 s13, s13, 0
	s_waitcnt vmcnt(11)
; __device__ __forceinline__ unsigned pk2(float lo, float hi) { unsigned r; asm("v_cvt_pk_bf16_f32 %0, %1, %2" : "=v"(r) : "v"(lo), "v"(hi)); return r; }
; __device__ __forceinline__ void cf_sample_item(const bf16_t* PROJ, int s, int c, const float* st, const float* cw, const float* cb, bf16_t* CONVOUT, float* state_out) {
;     ...
; #pragma unroll
;     for (int t = 0; t < 4; ++t) { f32x2 acc = bias;
; #pragma unroll
;         for (int i = 0; i < 31; ++i) acc += xp[t + i] * w[i];
;         *(unsigned*)(CONVOUT + (size_t)(MP + 4 * s + t) * DM + c) = pk2(acc.x, acc.y); }
; #pragma unroll
;     for (int i = 0; i < 30; ++i) *(f32x2*)(state_out + (size_t)i * DM + c) = xp[4 + i];
	v_mov_b32_e32 v200, v220
	v_mov_b32_e32 v201, v221
	v_mov_b32_e32 v202, v222
	v_mov_b32_e32 v203, v223
	v_mov_b32_e32 v204, v220
	v_mov_b32_e32 v205, v221
	v_mov_b32_e32 v206, v222
	v_mov_b32_e32 v207, v223
	v_mov_b32_e32 v208, v220
	v_mov_b32_e32 v209, v221
	v_mov_b32_e32 v210, v222
	v_mov_b32_e32 v211, v223
	v_mov_b32_e32 v216, v220
	v_mov_b32_e32 v217, v221
	v_mov_b32_e32 v218, v222
	v_mov_b32_e32 v219, v223
	v_pk_fma_f32 v[200:201], v[124:125], v[0:1], v[200:201]
	v_pk_fma_f32 v[202:203], v[126:127], v[2:3], v[202:203]
	global_load_dwordx4 v[124:127], v224, s[12:13]
	s_add_u32 s12, s12, 0x2000
	s_addc_u32 s13, s13, 0
	s_waitcnt vmcnt(11)
	v_pk_fma_f32 v[200:201], v[128:129], v[4:5], v[200:201]
	v_pk_fma_f32 v[202:203], v[130:131], v[6:7], v[202:203]
	v_pk_fma_f32 v[204:205], v[128:129], v[0:1], v[204:205]
	v_pk_fma_f32 v[206:207], v[130:131], v[2:3], v[206:207]
	global_load_dwordx4 v[128:131], v224, s[12:13]
	s_add_u32 s12, s12, 0x2000
	s_addc_u32 s13, s13, 0
	s_waitcnt vmcnt(11)
	v_pk_fma_f32 v[200:201], v[132:133], v[8:9], v[200:201]
	v_pk_fma_f32 v[202:203], v[134:135], v[10:11], v[202:203]
	v_pk_fma_f32 v[204:205], v[132:133], v[4:5], v[204:205]
	v_pk_fma_f32 v[206:207], v[134:135], v[6:7], v[206:207]
	v_pk_fma_f32 v[208:209], v[132:133], v[0:1], v[208:209]
	v_pk_fma_f32 v[210:211], v[134:135], v[2:3], v[210:211]
	global_load_dwordx4 v[132:135], v224, s[12:13]
	s_add_u32 s12, s12, 0x2000
	s_addc_u32 s13, s13, 0
	s_waitcnt vmcnt(11)
	v_pk_fma_f32 v[200:201], v[136:137], v[12:13], v[200:201]
	v_pk_fma_f32 v[202:203], v[138:139], v[14:15], v[202:203]
	v_pk_fma_f32 v[204:205], v[136:137], v[8:9], v[204:205]
	v_pk_fma_f32 v[206:207], v[138:139], v[10:11], v[206:207]
	v_pk_fma_f32 v[208:209], v[136:137], v[4:5], v[208:209]
	v_pk_fma_f32 v[210:211], v[138:139], v[6:7], v[210:211]
	v_pk_fma_f32 v[216:217], v[136:137], v[0:1], v[216:217]
	v_pk_fma_f32 v[218:219], v[138:139], v[2:3], v[218:219]
	global_load_dwordx4 v[136:139], v224, s[12:13]
	s_add_u32 s12, s12, 0x2000
	s_addc_u32 s13, s13, 0
	s_waitcnt vmcnt(11)
	v_pk_fma_f32 v[200:201], v[140:141], v[16:17], v[200:201]
	v_pk_fma_f32 v[202:203], v[142:143], v[18:19], v[202:203]
	v_pk_fma_f32 v[204:205], v[140:141], v[12:13], v[204:205]
	v_pk_fma_f32 v[206:207], v[142:143], v[14:15], v[206:207]
	v_pk_fma_f32 v[208:209], v[140:141], v[8:9], v[208:209]
	v_pk_fma_f32 v[210:211], v[142:143], v[10:11], v[210:211]
	v_pk_fma_f32 v[216:217], v[140:141], v[4:5], v[216:217]
	v_pk_fma_f32 v[218:219], v[142:143], v[6:7], v[218:219]
	global_store_dwordx4 v224, v[140:143], s[14:15]
	s_add_u32 s14, s14, 0x2000
	s_addc_u32 s15, s15, 0
	global_load_dwordx4 v[140:143], v224, s[12:13]
	s_add_u32 s12, s12, 0x2000
	s_addc_u32 s13, s13, 0
	s_waitcnt vmcnt(12)
	v_pk_fma_f32 v[200:201], v[144:145], v[20:21], v[200:201]
	v_pk_fma_f32 v[202:203], v[146:147], v[22:23], v[202:203]
	v_pk_fma_f32 v[204:205], v[144:145], v[16:17], v[204:205]
	v_pk_fma_f32 v[206:207], v[146:147], v[18:19], v[206:207]
	v_pk_fma_f32 v[208:209], v[144:145], v[12:13], v[208:209]
	v_pk_fma_f32 v[210:211], v[146:147], v[14:15], v[210:211]
	v_pk_fma_f32 v[216:217], v[144:145], v[8:9], v[216:217]
	v_pk_fma_f32 v[218:219], v[146:147], v[10:11], v[218:219]
	global_store_dwordx4 v224, v[144:147], s[14:15]
	s_add_u32 s14, s14, 0x2000
	s_addc_u32 s15, s15, 0
	global_load_dwordx4 v[144:147], v224, s[12:13]
	s_add_u32 s12, s12, 0x2000
	s_addc_u32 s13, s13, 0
	s_waitcnt vmcnt(13)
	v_pk_fma_f32 v[200:201], v[148:149], v[24:25], v[200:201]
	v_pk_fma_f32 v[202:203], v[150:151], v[26:27], v[202:203]
	v_pk_fma_f32 v[204:205], v[148:149], v[20:21], v[204:205]
	v_pk_fma_f32 v[206:207], v[150:151], v[22:23], v[206:207]
	v_pk_fma_f32 v[208:209], v[148:149], v[16:17], v[208:209]
	v_pk_fma_f32 v[210:211], v[150:151], v[18:19], v[210:211]
	v_pk_fma_f32 v[216:217], v[148:149], v[12:13], v[216:217]
	v_pk_fma_f32 v[218:219], v[150:151], v[14:15], v[218:219]
	global_store_dwordx4 v224, v[148:151], s[14:15]
	s_add_u32 s14, s14, 0x2000
	s_addc_u32 s15, s15, 0
	global_load_dwordx4 v[148:151], v224, s[12:13]
	s_add_u32 s12, s12, 0x2000
	s_addc_u32 s13, s13, 0
	s_waitcnt vmcnt(14)
	v_pk_fma_f32 v[200:201], v[152:153], v[28:29], v[200:201]
	v_pk_fma_f32 v[202:203], v[154:155], v[30:31], v[202:203]
	v_pk_fma_f32 v[204:205], v[152:153], v[24:25], v[204:205]
	v_pk_fma_f32 v[206:207], v[154:155], v[26:27], v[206:207]
	v_pk_fma_f32 v[208:209], v[152:153], v[20:21], v[208:209]
	v_pk_fma_f32 v[210:211], v[154:155], v[22:23], v[210:211]
	v_pk_fma_f32 v[216:217], v[152:153], v[16:17], v[216:217]
	v_pk_fma_f32 v[218:219], v[154:155], v[18:19], v[218:219]
	global_store_dwordx4 v224, v[152:155], s[14:15]
	s_add_u32 s14, s14, 0x2000
	s_addc_u32 s15, s15, 0
	global_load_dwordx4 v[152:155], v224, s[12:13]
	s_add_u32 s12, s12, 0x2000
	s_addc_u32 s13, s13, 0
	s_waitcnt vmcnt(15)
	v_pk_fma_f32 v[200:201], v[156:157], v[32:33], v[200:201]
	v_pk_fma_f32 v[202:203], v[158:159], v[34:35], v[202:203]
	v_pk_fma_f32 v[204:205], v[156:157], v[28:29], v[204:205]
	v_pk_fma_f32 v[206:207], v[158:159], v[30:31], v[206:207]
	v_pk_fma_f32 v[208:209], v[156:157], v[24:25], v[208:209]
	v_pk_fma_f32 v[210:211], v[158:159], v[26:27], v[210:211]
	v_pk_fma_f32 v[216:217], v[156:157], v[20:21], v[216:217]
	v_pk_fma_f32 v[218:219], v[158:159], v[22:23], v[218:219]
	global_store_dwordx4 v224, v[156:159], s[14:15]
	s_add_u32 s14, s14, 0x2000
	s_addc_u32 s15, s15, 0
	global_load_dwordx4 v[156:159], v224, s[12:13]
	s_add_u32 s12, s12, 0x2000
	s_addc_u32 s13, s13, 0
	s_waitcnt vmcnt(16)
; __device__ __forceinline__ unsigned pk2(float lo, float hi) { unsigned r; asm("v_cvt_pk_bf16_f32 %0, %1, %2" : "=v"(r) : "v"(lo), "v"(hi)); return r; }
; __device__ __forceinline__ void cf_sample_item(const bf16_t* PROJ, int s, int c, const float* st, const float* cw, const float* cb, bf16_t* CONVOUT, float* state_out) {
;     ...
; #pragma unroll
;     for (int t = 0; t < 4; ++t) { f32x2 acc = bias;
; #pragma unroll
;         for (int i = 0; i < 31; ++i) acc += xp[t + i] * w[i];
;         *(unsigned*)(CONVOUT + (size_t)(MP + 4 * s + t) * DM + c) = pk2(acc.x, acc.y); }
; #pragma unroll
;     for (int i = 0; i < 30; ++i) *(f32x2*)(state_out + (size_t)i * DM + c) = xp[4 + i];
	v_pk_fma_f32 v[200:201], v[160:161], v[36:37], v[200:201]
	v_pk_fma_f32 v[202:203], v[162:163], v[38:39], v[202:203]
	v_pk_fma_f32 v[204:205], v[160:161], v[32:33], v[204:205]
	v_pk_fma_f32 v[206:207], v[162:163], v[34:35], v[206:207]
	v_pk_fma_f32 v[208:209], v[160:161], v[28:29], v[208:209]
	v_pk_fma_f32 v[210:211], v[162:163], v[30:31], v[210:211]
	v_pk_fma_f32 v[216:217], v[160:161], v[24:25], v[216:217]
	v_pk_fma_f32 v[218:219], v[162:163], v[26:27], v[218:219]
	global_store_dwordx4 v224, v[160:163], s[14:15]
	s_add_u32 s14, s14, 0x2000
	s_addc_u32 s15, s15, 0
	global_load_dwordx4 v[160:163], v224, s[12:13]
	s_add_u32 s12, s12, 0x2000
	s_addc_u32 s13, s13, 0
	s_waitcnt vmcnt(17)
	v_pk_fma_f32 v[200:201], v[164:165], v[40:41], v[200:201]
	v_pk_fma_f32 v[202:203], v[166:167], v[42:43], v[202:203]
	v_pk_fma_f32 v[204:205], v[164:165], v[36:37], v[204:205]
	v_pk_fma_f32 v[206:207], v[166:167], v[38:39], v[206:207]
	v_pk_fma_f32 v[208:209], v[164:165], v[32:33], v[208:209]
	v_pk_fma_f32 v[210:211], v[166:167], v[34:35], v[210:211]
	v_pk_fma_f32 v[216:217], v[164:165], v[28:29], v[216:217]
	v_pk_fma_f32 v[218:219], v[166:167], v[30:31], v[218:219]
	global_store_dwordx4 v224, v[164:167], s[14:15]
	s_add_u32 s14, s14, 0x2000
	s_addc_u32 s15, s15, 0
	global_load_dwordx4 v[164:167], v224, s[12:13]
	s_add_u32 s12, s12, 0x2000
	s_addc_u32 s13, s13, 0
	s_waitcnt vmcnt(18)
	v_pk_fma_f32 v[200:201], v[168:169], v[44:45], v[200:201]
	v_pk_fma_f32 v[202:203], v[170:171], v[46:47], v[202:203]
	v_pk_fma_f32 v[204:205], v[168:169], v[40:41], v[204:205]
	v_pk_fma_f32 v[206:207], v[170:171], v[42:43], v[206:207]
	v_pk_fma_f32 v[208:209], v[168:169], v[36:37], v[208:209]
	v_pk_fma_f32 v[210:211], v[170:171], v[38:39], v[210:211]
	v_pk_fma_f32 v[216:217], v[168:169], v[32:33], v[216:217]
	v_pk_fma_f32 v[218:219], v[170:171], v[34:35], v[218:219]
	global_store_dwordx4 v224, v[168:171], s[14:15]
	s_add_u32 s14, s14, 0x2000
	s_addc_u32 s15, s15, 0
	global_load_dwordx4 v[168:171], v224, s[12:13]
	s_add_u32 s12, s12, 0x2000
	s_addc_u32 s13, s13, 0
	s_waitcnt vmcnt(19)
	v_pk_fma_f32 v[200:201], v[124:125], v[48:49], v[200:201]
	v_pk_fma_f32 v[202:203], v[126:127], v[50:51], v[202:203]
	v_pk_fma_f32 v[204:205], v[124:125], v[44:45], v[204:205]
	v_pk_fma_f32 v[206:207], v[126:127], v[46:47], v[206:207]
	v_pk_fma_f32 v[208:209], v[124:125], v[40:41], v[208:209]
	v_pk_fma_f32 v[210:211], v[126:127], v[42:43], v[210:211]
	v_pk_fma_f32 v[216:217], v[124:125], v[36:37], v[216:217]
	v_pk_fma_f32 v[218:219], v[126:127], v[38:39], v[218:219]
	global_store_dwordx4 v224, v[124:127], s[14:15]
	s_add_u32 s14, s14, 0x2000
	s_addc_u32 s15, s15, 0
	global_load_dwordx4 v[124:127], v224, s[12:13]
	s_add_u32 s12, s12, 0x2000
	s_addc_u32 s13, s13, 0
	s_waitcnt vmcnt(20)
	v_pk_fma_f32 v[200:201], v[128:129], v[52:53], v[200:201]
	v_pk_fma_f32 v[202:203], v[130:131], v[54:55], v[202:203]
	v_pk_fma_f32 v[204:205], v[128:129], v[48:49], v[204:205]
	v_pk_fma_f32 v[206:207], v[130:131], v[50:51], v[206:207]
	v_pk_fma_f32 v[208:209], v[128:129], v[44:45], v[208:209]
	v_pk_fma_f32 v[210:211], v[130:131], v[46:47], v[210:211]
	v_pk_fma_f32 v[216:217], v[128:129], v[40:41], v[216:217]
	v_pk_fma_f32 v[218:219], v[130:131], v[42:43], v[218:219]
	global_store_dwordx4 v224, v[128:131], s[14:15]
	s_add_u32 s14, s14, 0x2000
	s_addc_u32 s15, s15, 0
	global_load_dwordx4 v[128:131], v224, s[12:13]
	s_add_u32 s12, s12, 0x2000
	s_addc_u32 s13, s13, 0
	s_waitcnt vmcnt(21)
	v_pk_fma_f32 v[200:201], v[132:133], v[56:57], v[200:201]
	v_pk_fma_f32 v[202:203], v[134:135], v[58:59], v[202:203]
	v_pk_fma_f32 v[204:205], v[132:133], v[52:53], v[204:205]
	v_pk_fma_f32 v[206:207], v[134:135], v[54:55], v[206:207]
	v_pk_fma_f32 v[208:209], v[132:133], v[48:49], v[208:209]
	v_pk_fma_f32 v[210:211], v[134:135], v[50:51], v[210:211]
	v_pk_fma_f32 v[216:217], v[132:133], v[44:45], v[216:217]
	v_pk_fma_f32 v[218:219], v[134:135], v[46:47], v[218:219]
	global_store_dwordx4 v224, v[132:135], s[14:15]
	s_add_u32 s14, s14, 0x2000
	s_addc_u32 s15, s15, 0
	global_load_dwordx4 v[132:135], v224, s[12:13]
	s_add_u32 s12, s12, 0x2000
	s_addc_u32 s13, s13, 0
	s_waitcnt vmcnt(22)
	v_pk_fma_f32 v[200:201], v[136:137], v[60:61], v[200:201]
	v_pk_fma_f32 v[202:203], v[138:139], v[62:63], v[202:203]
	v_pk_fma_f32 v[204:205], v[136:137], v[56:57], v[204:205]
	v_pk_fma_f32 v[206:207], v[138:139], v[58:59], v[206:207]
	v_pk_fma_f32 v[208:209], v[136:137], v[52:53], v[208:209]
	v_pk_fma_f32 v[210:211], v[138:139], v[54:55], v[210:211]
	v_pk_fma_f32 v[216:217], v[136:137], v[48:49], v[216:217]
	v_pk_fma_f32 v[218:219], v[138:139], v[50:51], v[218:219]
	global_store_dwordx4 v224, v[136:139], s[14:15]
	s_add_u32 s14, s14, 0x2000
	s_addc_u32 s15, s15, 0
	global_load_dwordx4 v[136:139], v224, s[12:13]
	s_add_u32 s12, s12, 0x2000
	s_addc_u32 s13, s13, 0
	s_waitcnt vmcnt(22)
	v_pk_fma_f32 v[200:201], v[140:141], v[64:65], v[200:201]
	v_pk_fma_f32 v[202:203], v[142:143], v[66:67], v[202:203]
	v_pk_fma_f32 v[204:205], v[140:141], v[60:61], v[204:205]
	v_pk_fma_f32 v[206:207], v[142:143], v[62:63], v[206:207]
	v_pk_fma_f32 v[208:209], v[140:141], v[56:57], v[208:209]
	v_pk_fma_f32 v[210:211], v[142:143], v[58:59], v[210:211]
	v_pk_fma_f32 v[216:217], v[140:141], v[52:53], v[216:217]
	v_pk_fma_f32 v[218:219], v[142:143], v[54:55], v[218:219]
	global_store_dwordx4 v224, v[140:143], s[14:15]
	s_add_u32 s14, s14, 0x2000
	s_addc_u32 s15, s15, 0
	global_load_dwordx4 v[140:143], v224, s[12:13]
	s_add_u32 s12, s12, 0x2000
	s_addc_u32 s13, s13, 0
	s_waitcnt vmcnt(22)
; __device__ __forceinline__ unsigned pk2(float lo, float hi) { unsigned r; asm("v_cvt_pk_bf16_f32 %0, %1, %2" : "=v"(r) : "v"(lo), "v"(hi)); return r; }
; __device__ __forceinline__ void cf_sample_item(const bf16_t* PROJ, int s, int c, const float* st, const float* cw, const float* cb, bf16_t* CONVOUT, float* state_out) {
;     ...
; #pragma unroll
;     for (int t = 0; t < 4; ++t) { f32x2 acc = bias;
; #pragma unroll
;         for (int i = 0; i < 31; ++i) acc += xp[t + i] * w[i];
;         *(unsigned*)(CONVOUT + (size_t)(MP + 4 * s + t) * DM + c) = pk2(acc.x, acc.y); }
; #pragma unroll
;     for (int i = 0; i < 30; ++i) *(f32x2*)(state_out + (size_t)i * DM + c) = xp[4 + i];
	v_pk_fma_f32 v[200:201], v[144:145], v[68:69], v[200:201]
	v_pk_fma_f32 v[202:203], v[146:147], v[70:71], v[202:203]
	v_pk_fma_f32 v[204:205], v[144:145], v[64:65], v[204:205]
	v_pk_fma_f32 v[206:207], v[146:147], v[66:67], v[206:207]
	v_pk_fma_f32 v[208:209], v[144:145], v[60:61], v[208:209]
	v_pk_fma_f32 v[210:211], v[146:147], v[62:63], v[210:211]
	v_pk_fma_f32 v[216:217], v[144:145], v[56:57], v[216:217]
	v_pk_fma_f32 v[218:219], v[146:147], v[58:59], v[218:219]
	global_store_dwordx4 v224, v[144:147], s[14:15]
	s_add_u32 s14, s14, 0x2000
	s_addc_u32 s15, s15, 0
	global_load_dwordx4 v[144:147], v224, s[12:13]
	s_add_u32 s12, s12, 0x2000
	s_addc_u32 s13, s13, 0
	s_waitcnt vmcnt(22)
	v_pk_fma_f32 v[200:201], v[148:149], v[72:73], v[200:201]
	v_pk_fma_f32 v[202:203], v[150:151], v[74:75], v[202:203]
	v_pk_fma_f32 v[204:205], v[148:149], v[68:69], v[204:205]
	v_pk_fma_f32 v[206:207], v[150:151], v[70:71], v[206:207]
	v_pk_fma_f32 v[208:209], v[148:149], v[64:65], v[208:209]
	v_pk_fma_f32 v[210:211], v[150:151], v[66:67], v[210:211]
	v_pk_fma_f32 v[216:217], v[148:149], v[60:61], v[216:217]
	v_pk_fma_f32 v[218:219], v[150:151], v[62:63], v[218:219]
	global_store_dwordx4 v224, v[148:151], s[14:15]
	s_add_u32 s14, s14, 0x2000
	s_addc_u32 s15, s15, 0
	s_waitcnt vmcnt(21)
	v_pk_fma_f32 v[200:201], v[152:153], v[76:77], v[200:201]
	v_pk_fma_f32 v[202:203], v[154:155], v[78:79], v[202:203]
	v_pk_fma_f32 v[204:205], v[152:153], v[72:73], v[204:205]
	v_pk_fma_f32 v[206:207], v[154:155], v[74:75], v[206:207]
	v_pk_fma_f32 v[208:209], v[152:153], v[68:69], v[208:209]
	v_pk_fma_f32 v[210:211], v[154:155], v[70:71], v[210:211]
	v_pk_fma_f32 v[216:217], v[152:153], v[64:65], v[216:217]
	v_pk_fma_f32 v[218:219], v[154:155], v[66:67], v[218:219]
	global_store_dwordx4 v224, v[152:155], s[14:15]
	s_add_u32 s14, s14, 0x2000
	s_addc_u32 s15, s15, 0
	s_waitcnt vmcnt(20)
	v_pk_fma_f32 v[200:201], v[156:157], v[80:81], v[200:201]
	v_pk_fma_f32 v[202:203], v[158:159], v[82:83], v[202:203]
	v_pk_fma_f32 v[204:205], v[156:157], v[76:77], v[204:205]
	v_pk_fma_f32 v[206:207], v[158:159], v[78:79], v[206:207]
	v_pk_fma_f32 v[208:209], v[156:157], v[72:73], v[208:209]
	v_pk_fma_f32 v[210:211], v[158:159], v[74:75], v[210:211]
	v_pk_fma_f32 v[216:217], v[156:157], v[68:69], v[216:217]
	v_pk_fma_f32 v[218:219], v[158:159], v[70:71], v[218:219]
	global_store_dwordx4 v224, v[156:159], s[14:15]
	s_add_u32 s14, s14, 0x2000
	s_addc_u32 s15, s15, 0
	s_waitcnt vmcnt(19)
	v_pk_fma_f32 v[200:201], v[160:161], v[84:85], v[200:201]
	v_pk_fma_f32 v[202:203], v[162:163], v[86:87], v[202:203]
	v_pk_fma_f32 v[204:205], v[160:161], v[80:81], v[204:205]
	v_pk_fma_f32 v[206:207], v[162:163], v[82:83], v[206:207]
	v_pk_fma_f32 v[208:209], v[160:161], v[76:77], v[208:209]
	v_pk_fma_f32 v[210:211], v[162:163], v[78:79], v[210:211]
	v_pk_fma_f32 v[216:217], v[160:161], v[72:73], v[216:217]
	v_pk_fma_f32 v[218:219], v[162:163], v[74:75], v[218:219]
	global_store_dwordx4 v224, v[160:163], s[14:15]
	s_add_u32 s14, s14, 0x2000
	s_addc_u32 s15, s15, 0
	s_waitcnt vmcnt(18)
	v_pk_fma_f32 v[200:201], v[164:165], v[88:89], v[200:201]
	v_pk_fma_f32 v[202:203], v[166:167], v[90:91], v[202:203]
	v_pk_fma_f32 v[204:205], v[164:165], v[84:85], v[204:205]
	v_pk_fma_f32 v[206:207], v[166:167], v[86:87], v[206:207]
	v_pk_fma_f32 v[208:209], v[164:165], v[80:81], v[208:209]
	v_pk_fma_f32 v[210:211], v[166:167], v[82:83], v[210:211]
	v_pk_fma_f32 v[216:217], v[164:165], v[76:77], v[216:217]
	v_pk_fma_f32 v[218:219], v[166:167], v[78:79], v[218:219]
	global_store_dwordx4 v224, v[164:167], s[14:15]
	s_add_u32 s14, s14, 0x2000
	s_addc_u32 s15, s15, 0
	s_waitcnt vmcnt(17)
	v_pk_fma_f32 v[200:201], v[168:169], v[92:93], v[200:201]
	v_pk_fma_f32 v[202:203], v[170:171], v[94:95], v[202:203]
	v_pk_fma_f32 v[204:205], v[168:169], v[88:89], v[204:205]
	v_pk_fma_f32 v[206:207], v[170:171], v[90:91], v[206:207]
	v_pk_fma_f32 v[208:209], v[168:169], v[84:85], v[208:209]
	v_pk_fma_f32 v[210:211], v[170:171], v[86:87], v[210:211]
	v_pk_fma_f32 v[216:217], v[168:169], v[80:81], v[216:217]
	v_pk_fma_f32 v[218:219], v[170:171], v[82:83], v[218:219]
	global_store_dwordx4 v224, v[168:171], s[14:15]
	s_add_u32 s14, s14, 0x2000
	s_addc_u32 s15, s15, 0
	s_waitcnt vmcnt(16)
	v_pk_fma_f32 v[200:201], v[124:125], v[96:97], v[200:201]
	v_pk_fma_f32 v[202:203], v[126:127], v[98:99], v[202:203]
	v_pk_fma_f32 v[204:205], v[124:125], v[92:93], v[204:205]
	v_pk_fma_f32 v[206:207], v[126:127], v[94:95], v[206:207]
	v_pk_fma_f32 v[208:209], v[124:125], v[88:89], v[208:209]
	v_pk_fma_f32 v[210:211], v[126:127], v[90:91], v[210:211]
	v_pk_fma_f32 v[216:217], v[124:125], v[84:85], v[216:217]
	v_pk_fma_f32 v[218:219], v[126:127], v[86:87], v[218:219]
	global_store_dwordx4 v224, v[124:127], s[14:15]
	s_add_u32 s14, s14, 0x2000
	s_addc_u32 s15, s15, 0
	s_waitcnt vmcnt(15)
	v_pk_fma_f32 v[200:201], v[128:129], v[100:101], v[200:201]
	v_pk_fma_f32 v[202:203], v[130:131], v[102:103], v[202:203]
	v_pk_fma_f32 v[204:205], v[128:129], v[96:97], v[204:205]
	v_pk_fma_f32 v[206:207], v[130:131], v[98:99], v[206:207]
	v_pk_fma_f32 v[208:209], v[128:129], v[92:93], v[208:209]
	v_pk_fma_f32 v[210:211], v[130:131], v[94:95], v[210:211]
	v_pk_fma_f32 v[216:217], v[128:129], v[88:89], v[216:217]
	v_pk_fma_f32 v[218:219], v[130:131], v[90:91], v[218:219]
	global_store_dwordx4 v224, v[128:131], s[14:15]
	s_add_u32 s14, s14, 0x2000
	s_addc_u32 s15, s15, 0
	s_waitcnt vmcnt(14)
; __device__ __forceinline__ float bf2f(unsigned h) { return __uint_as_float(h << 16); }
; __device__ __forceinline__ unsigned pk2(float lo, float hi) { unsigned r; asm("v_cvt_pk_bf16_f32 %0, %1, %2" : "=v"(r) : "v"(lo), "v"(hi)); return r; }
; __device__ __forceinline__ void cf_sample_item(const bf16_t* PROJ, int s, int c, const float* st, const float* cw, const float* cb, bf16_t* CONVOUT, float* state_out) {
;     ...
; #pragma unroll
;     for (int t = 0; t < 4; ++t) { xp[30 + t].x = bf2f(uv[t] & 0xffffu); xp[30 + t].y = bf2f(uv[t] >> 16); }
; #pragma unroll
;     for (int t = 0; t < 4; ++t) { f32x2 acc = bias;
; #pragma unroll
;         for (int i = 0; i < 31; ++i) acc += xp[t + i] * w[i];
;         *(unsigned*)(CONVOUT + (size_t)(MP + 4 * s + t) * DM + c) = pk2(acc.x, acc.y); }
; #pragma unroll
;     for (int i = 0; i < 30; ++i) *(f32x2*)(state_out + (size_t)i * DM + c) = xp[4 + i];
; __global__ void __launch_bounds__(512, 2) mk_fwd(Args args) {
;     ...
;             for (int it2 = bx; it2 < 256; it2 += G) { const int s = it2 >> 1, c = (it2 & 1) * 1024 + tid * 2;
	v_pk_fma_f32 v[200:201], v[132:133], v[104:105], v[200:201]
	v_pk_fma_f32 v[202:203], v[134:135], v[106:107], v[202:203]
	v_pk_fma_f32 v[204:205], v[132:133], v[100:101], v[204:205]
	v_pk_fma_f32 v[206:207], v[134:135], v[102:103], v[206:207]
	v_pk_fma_f32 v[208:209], v[132:133], v[96:97], v[208:209]
	v_pk_fma_f32 v[210:211], v[134:135], v[98:99], v[210:211]
	v_pk_fma_f32 v[216:217], v[132:133], v[92:93], v[216:217]
	v_pk_fma_f32 v[218:219], v[134:135], v[94:95], v[218:219]
	global_store_dwordx4 v224, v[132:135], s[14:15]
	s_add_u32 s14, s14, 0x2000
	s_addc_u32 s15, s15, 0
	s_waitcnt vmcnt(13)
	v_pk_fma_f32 v[200:201], v[136:137], v[108:109], v[200:201]
	v_pk_fma_f32 v[202:203], v[138:139], v[110:111], v[202:203]
	v_pk_fma_f32 v[204:205], v[136:137], v[104:105], v[204:205]
	v_pk_fma_f32 v[206:207], v[138:139], v[106:107], v[206:207]
	v_pk_fma_f32 v[208:209], v[136:137], v[100:101], v[208:209]
	v_pk_fma_f32 v[210:211], v[138:139], v[102:103], v[210:211]
	v_pk_fma_f32 v[216:217], v[136:137], v[96:97], v[216:217]
	v_pk_fma_f32 v[218:219], v[138:139], v[98:99], v[218:219]
	global_store_dwordx4 v224, v[136:139], s[14:15]
	s_add_u32 s14, s14, 0x2000
	s_addc_u32 s15, s15, 0
	s_waitcnt vmcnt(12)
	v_pk_fma_f32 v[200:201], v[140:141], v[112:113], v[200:201]
	v_pk_fma_f32 v[202:203], v[142:143], v[114:115], v[202:203]
	v_pk_fma_f32 v[204:205], v[140:141], v[108:109], v[204:205]
	v_pk_fma_f32 v[206:207], v[142:143], v[110:111], v[206:207]
	v_pk_fma_f32 v[208:209], v[140:141], v[104:105], v[208:209]
	v_pk_fma_f32 v[210:211], v[142:143], v[106:107], v[210:211]
	v_pk_fma_f32 v[216:217], v[140:141], v[100:101], v[216:217]
	v_pk_fma_f32 v[218:219], v[142:143], v[102:103], v[218:219]
	global_store_dwordx4 v224, v[140:143], s[14:15]
	s_add_u32 s14, s14, 0x2000
	s_addc_u32 s15, s15, 0
	s_waitcnt vmcnt(11)
	v_pk_fma_f32 v[200:201], v[144:145], v[116:117], v[200:201]
	v_pk_fma_f32 v[202:203], v[146:147], v[118:119], v[202:203]
	v_pk_fma_f32 v[204:205], v[144:145], v[112:113], v[204:205]
	v_pk_fma_f32 v[206:207], v[146:147], v[114:115], v[206:207]
	v_pk_fma_f32 v[208:209], v[144:145], v[108:109], v[208:209]
	v_pk_fma_f32 v[210:211], v[146:147], v[110:111], v[210:211]
	v_pk_fma_f32 v[216:217], v[144:145], v[104:105], v[216:217]
	v_pk_fma_f32 v[218:219], v[146:147], v[106:107], v[218:219]
	global_store_dwordx4 v224, v[144:147], s[14:15]
	s_add_u32 s14, s14, 0x2000
	s_addc_u32 s15, s15, 0
	v_lshlrev_b32_e32 v184, 16, v174
	v_and_b32_e32 v185, 0xffff0000, v174
	v_lshlrev_b32_e32 v186, 16, v175
	v_and_b32_e32 v187, 0xffff0000, v175
	v_lshlrev_b32_e32 v188, 16, v176
	v_and_b32_e32 v189, 0xffff0000, v176
	v_lshlrev_b32_e32 v190, 16, v177
	v_and_b32_e32 v191, 0xffff0000, v177
	v_lshlrev_b32_e32 v192, 16, v178
	v_and_b32_e32 v193, 0xffff0000, v178
	v_lshlrev_b32_e32 v194, 16, v179
	v_and_b32_e32 v195, 0xffff0000, v179
	v_lshlrev_b32_e32 v196, 16, v180
	v_and_b32_e32 v197, 0xffff0000, v180
	v_lshlrev_b32_e32 v198, 16, v181
	v_and_b32_e32 v199, 0xffff0000, v181
	v_pk_fma_f32 v[200:201], v[184:185], v[120:121], v[200:201]
	v_pk_fma_f32 v[202:203], v[186:187], v[122:123], v[202:203]
	v_pk_fma_f32 v[204:205], v[184:185], v[116:117], v[204:205]
	v_pk_fma_f32 v[206:207], v[186:187], v[118:119], v[206:207]
	v_pk_fma_f32 v[208:209], v[184:185], v[112:113], v[208:209]
	v_pk_fma_f32 v[210:211], v[186:187], v[114:115], v[210:211]
	v_pk_fma_f32 v[216:217], v[184:185], v[108:109], v[216:217]
	v_pk_fma_f32 v[218:219], v[186:187], v[110:111], v[218:219]
	global_store_dwordx4 v224, v[184:187], s[14:15]
	s_add_u32 s14, s14, 0x2000
	s_addc_u32 s15, s15, 0
	v_pk_fma_f32 v[204:205], v[188:189], v[120:121], v[204:205]
	v_pk_fma_f32 v[206:207], v[190:191], v[122:123], v[206:207]
	v_pk_fma_f32 v[208:209], v[188:189], v[116:117], v[208:209]
	v_pk_fma_f32 v[210:211], v[190:191], v[118:119], v[210:211]
	v_pk_fma_f32 v[216:217], v[188:189], v[112:113], v[216:217]
	v_pk_fma_f32 v[218:219], v[190:191], v[114:115], v[218:219]
	global_store_dwordx4 v224, v[188:191], s[14:15]
	s_add_u32 s14, s14, 0x2000
	s_addc_u32 s15, s15, 0
	v_pk_fma_f32 v[208:209], v[192:193], v[120:121], v[208:209]
	v_pk_fma_f32 v[210:211], v[194:195], v[122:123], v[210:211]
	v_pk_fma_f32 v[216:217], v[192:193], v[116:117], v[216:217]
	v_pk_fma_f32 v[218:219], v[194:195], v[118:119], v[218:219]
	global_store_dwordx4 v224, v[192:195], s[14:15]
	s_add_u32 s14, s14, 0x2000
	s_addc_u32 s15, s15, 0
	v_pk_fma_f32 v[216:217], v[196:197], v[120:121], v[216:217]
	v_pk_fma_f32 v[218:219], v[198:199], v[122:123], v[218:219]
	global_store_dwordx4 v224, v[196:199], s[14:15]
	s_add_u32 s14, s14, 0x2000
	s_addc_u32 s15, s15, 0
	v_cvt_pk_bf16_f32 v226, v200, v201
	v_cvt_pk_bf16_f32 v227, v202, v203
	global_store_dwordx2 v225, v[226:227], s[36:37]
	s_add_u32 s36, s36, 0x1000
	s_addc_u32 s37, s37, 0
	v_cvt_pk_bf16_f32 v226, v204, v205
	v_cvt_pk_bf16_f32 v227, v206, v207
	global_store_dwordx2 v225, v[226:227], s[36:37]
	s_add_u32 s36, s36, 0x1000
	s_addc_u32 s37, s37, 0
	v_cvt_pk_bf16_f32 v226, v208, v209
	v_cvt_pk_bf16_f32 v227, v210, v211
	global_store_dwordx2 v225, v[226:227], s[36:37]
	s_add_u32 s36, s36, 0x1000
	s_addc_u32 s37, s37, 0
	v_cvt_pk_bf16_f32 v226, v216, v217
	v_cvt_pk_bf16_f32 v227, v218, v219
	global_store_dwordx2 v225, v[226:227], s[36:37]
	s_add_u32 s1, s1, s94
	s_cmpk_lt_u32 s1, 256
	s_cbranch_scc1 .Lcfs_item
.Lcfs_done:
.LBB0_296:
	s_waitcnt vmcnt(0)
	s_waitcnt vmcnt(0) lgkmcnt(0)
	s_barrier
	s_mov_b64 s[0:1], exec
	v_readlane_b32 s4, v253, 4
	v_readlane_b32 s5, v253, 5
	s_and_b64 s[4:5], s[0:1], s[4:5]
	s_mov_b64 exec, s[4:5]
	s_cbranch_execz .LBB0_348
	s_add_i32 s3, 0, 0x23fc0
	v_mov_b32_e32 v0, s3
	s_waitcnt vmcnt(0) expcnt(0) lgkmcnt(0)
	ds_read_b32 v2, v0
	s_add_i32 s3, 0, 0x23fc4
	v_mov_b32_e32 v0, s3
	ds_read_b32 v0, v0
	s_waitcnt lgkmcnt(1)
	v_cmp_ne_u32_e32 vcc, 0, v2
	s_cbranch_vccnz .LBB0_312
	v_readlane_b32 s4, v253, 0
	v_readlane_b32 s5, v253, 1
	s_load_dwordx2 s[8:9], s[4:5], 0x4
	s_add_u32 s4, s74, 0x1000
	s_addc_u32 s5, s75, 0
	s_add_u32 s6, s74, 0x1100
	s_addc_u32 s7, s75, 0
	s_waitcnt lgkmcnt(0)
	s_mul_i32 s3, s8, s94
	s_add_u32 s8, s74, 0x1200
	s_mul_i32 s3, s3, s9
	s_addc_u32 s9, s75, 0
	s_add_u32 s10, s74, 0x1300
	s_addc_u32 s11, s75, 0
	s_mov_b32 s28, 1
	v_mov_b32_e32 v16, 0
	s_branch .LBB0_300
